# WG stagger config C: as before plus 3.5us stagger of half the workgroups at phase 9 entry
# baseline (speedup 1.0000x reference)
;   DI bf16_t* z() const { return (bf16_t*)(ws + OFF_Z); }
; DI void phase_up(const Params& p, char* smem) {
;   float* rs = (float*)(smem + G_RSTD_OFF);
;   u32x4 ra[4], rb[4]; bool pre = false;
;   int rs_key = -1;
;   for (int t = blockIdx.x; t < 64 * 14; t += gridDim.x) {
;     const int mt = t & 63, nt = t >> 6, tn = t + gridDim.x;
;     const bool has_next = tn < 64 * 14;
;     const GTile tl = up_tile(p, t), nx = up_tile(p, has_next ? tn : t);
;     WAVE_GEOM;
;     const int mbase = mt * 256 + wm_ * 128;
;     if (nt < 6) {
;       f32x16 acc[2][4];
;       if (rs_key != mt * 2) { row_rstd(p.z(), LDZ1, 768, mt * 256, rs); rs_key = mt * 2; }
;       gemm_core<false>(tl, nx, has_next, has_next, pre, ra, rb, smem, acc);
.Lstag_9_0:
	s_cmpk_gt_i32 s84, 0x37f
	s_waitcnt lgkmcnt(0)
	s_barrier
	s_cbranch_scc1 .LBB0_1309
	s_add_u32 s0, s22, 0x80c0600
	s_addc_u32 s1, s23, 0
	s_add_u32 s8, s22, 0x35c0000
	s_addc_u32 s9, s23, 0
	s_add_u32 s10, s22, 0x80c0000
	s_addc_u32 s11, s23, 0
	s_add_u32 s12, s22, 0x3380000
	s_addc_u32 s13, s23, 0
	s_add_u32 s14, s22, 0x184c0000
	s_addc_u32 s15, s23, 0
	s_add_u32 s28, s22, 0x1a6c0000
	s_addc_u32 s29, s23, 0
	s_add_u32 s30, s22, 0x3fc0000
	s_addc_u32 s31, s23, 0
	s_add_u32 s34, s22, 0x154c0000
	s_addc_u32 s35, s23, 0
	s_add_u32 s36, s22, 0x80c0620
	s_addc_u32 s37, s23, 0
	s_lshl_b32 s24, s84, 8
	s_lshl_b32 s25, s96, 8
	s_add_u32 s38, s22, 0x80c0020
	v_writelane_b32 v252, s74, 4
	s_addc_u32 s39, s23, 0
	s_mov_b32 s65, -1
	s_mov_b64 s[2:3], 0
	s_mov_b32 s43, 0
	s_movk_i32 s27, 0x3300
	v_mov_b32_e32 v193, 0
	v_mov_b32_e32 v208, 0x358637bd
	s_mov_b32 s33, 0x800000
	s_movk_i32 s40, 0x1980
	s_mov_b32 s41, 0xcc000
	s_mov_b32 s56, 0x198000
	s_mov_b32 s57, 0x264000
	s_movk_i32 s58, 0x90
	s_mov_b64 s[44:45], 0xcc000
	s_mov_b64 s[46:47], 0x198000
	s_add_i32 s59, 16, 0x1b000
	s_mov_b32 s60, 0x44400000
	s_movk_i32 s61, 0xc00
	s_mov_b64 s[48:49], 0x154c0040
	v_mbcnt_hi_u32_b32 v209, -1, v207
	v_mov_b32_e32 v210, 0xf84
	v_mov_b32_e32 v211, 0x48
	v_mov_b32_e32 v212, 0x50
	v_mov_b32_e32 v213, 0x58
	v_mov_b32_e32 v214, 0x60
	v_mov_b32_e32 v215, 0x68
	v_mov_b32_e32 v216, 0x70
	v_mov_b32_e32 v217, 0x78
	s_mov_b32 s62, s84
	s_mov_b32 s4, s84
	s_mov_b32 s16, s84
	v_writelane_b32 v252, s75, 5
	s_branch .LBB0_972
